# v38 with the whole instruction stream shifted by 8 bytes (2 s_nop at entry): code placement trial
# speedup vs baseline: 1.0027x; 1.0027x over previous
; #define LAS __attribute__((address_space(3)))
; __global__ void __launch_bounds__(512, 2) fwd_mega(Args args) {
;     extern __shared__ __attribute__((aligned(16))) unsigned char lds_raw[];
;     LAS unsigned char* lds = (LAS unsigned char*)lds_raw;
;     cg::grid_group grid = cg::this_grid();
;     const int tid = threadIdx.x, lane = tid & 63, wave = __builtin_amdgcn_readfirstlane(tid >> 6);
;     const int G = gridDim.x, bx = blockIdx.x;
;     const float* x = args.in[0]; const float* mem = args.in[1]; const int* positions = (const int*)args.in[2];
;     float* out = args.out;
;     const int lo = args.ph_lo, hi = args.ph_hi;
;     ...
;     if (args.ph_lo < 0) grid.sync();
_Z8fwd_mega4Args:
	s_nop 0
	s_nop 0
	s_mov_b32 s96, s2
	s_load_dwordx4 s[84:87], s[0:1], 0x100
	s_load_dword s2, s[0:1], 0x110
	s_add_u32 s4, s0, 0x108
	s_addc_u32 s5, s1, 0
	v_and_b32_e32 v196, 0x3ff, v0
	s_waitcnt lgkmcnt(0)
	s_cmp_gt_i32 s84, -1
	v_writelane_b32 v249, s2, 0
	s_movk_i32 s2, 0x3ff
	v_readfirstlane_b32 s10, v196
	s_cbranch_scc1 .LBB0_12
	v_lshrrev_b32_e32 v1, 20, v0
	v_lshrrev_b32_e32 v0, 10, v0
	v_or_b32_e32 v0, v0, v1
	v_and_or_b32 v0, v0, s2, v196
	v_cmp_eq_u32_e32 vcc, 0, v0
	s_barrier
	s_and_saveexec_b64 s[2:3], vcc
	s_cbranch_execz .LBB0_11
	buffer_wbl2 sc1
	s_load_dwordx2 s[4:5], s[4:5], 0x58
	s_mov_b64 s[6:7], exec
	v_mbcnt_lo_u32_b32 v0, s6, 0
	v_mbcnt_hi_u32_b32 v0, s7, v0
	v_cmp_eq_u32_e32 vcc, 0, v0
	s_waitcnt lgkmcnt(0)
	s_load_dword s11, s[4:5], 0x28
	s_and_saveexec_b64 s[8:9], vcc
	s_cbranch_execz .LBB0_4
	s_bcnt1_i32_b64 s6, s[6:7]
	v_mov_b32_e32 v1, 0
	v_mov_b32_e32 v2, s6
	global_atomic_add v1, v1, v2, s[4:5] offset:32 sc0
